# diff-attention loop restructured: barrier rotated four PV MFMAs earlier (last PV group runs beside next tile's K reads and exps), K-fragment waits per MFMA, first V fragments prefetched under PV, LDS-
# speedup vs baseline: 1.0425x; 1.0087x over previous
.LBB0_365:
	v_mov_b32_e32 v26, v247
	s_ashr_i32 s14, s13, 6
	v_mov_b64_e32 v[18:19], s[8:9]
	v_readfirstlane_b32 s15, v26
	s_ashr_i32 s17, s15, 6
	s_ashr_i32 s21, s15, 7
	s_ashr_i32 s15, s14, 31
	s_lshl_b64 s[22:23], s[14:15], 11
	s_lshl_b32 s14, s13, 7
	s_and_b32 s14, s14, 0x780
	s_lshl_b32 s15, s21, 5
	s_and_b32 s16, s17, 1
	s_or_b32 s14, s22, s14
	s_ashr_i32 s20, s15, 31
	v_and_b32_e32 v195, 31, v26
	s_add_u32 s14, s14, s15
	s_addc_u32 s15, s23, s20
	v_or_b32_e32 v0, s14, v195
	s_lshl_b32 s20, s13, 3
	v_mad_u64_u32 v[20:21], s[24:25], v0, s91, v[18:19]
	s_and_b32 s20, s20, 0x180
	s_lshl_b32 s25, s16, 7
	s_lshl_b32 s24, s20, 1
	v_bfe_u32 v27, v26, 5, 1
	v_mad_i32_i24 v21, s15, v246, v21
	s_or_b32 s58, s25, s24
	v_lshl_add_u64 v[20:21], v[20:21], 0, s[58:59]
	v_lshlrev_b32_e32 v0, 4, v27
	v_lshl_add_u64 v[20:21], v[20:21], 0, v[0:1]
	global_load_dwordx4 v[130:133], v[20:21], off offset:1536
	global_load_dwordx4 v[134:137], v[20:21], off offset:1568
	global_load_dwordx4 v[138:141], v[20:21], off offset:1600
	global_load_dwordx4 v[142:145], v[20:21], off offset:1632
	v_bfe_u32 v20, v26, 3, 3
	v_lshl_or_b32 v20, s17, 3, v20
	v_lshrrev_b32_e32 v21, 1, v20
	v_xor_b32_e32 v28, v21, v26
	v_bfe_u32 v191, v26, 4, 2
	v_ashrrev_i32_e32 v21, 31, v20
	v_lshl_or_b32 v22, s17, 2, v191
	v_lshl_add_u64 v[20:21], s[22:23], 0, v[20:21]
	v_mad_u64_u32 v[24:25], s[26:27], v20, s91, v[18:19]
	v_ashrrev_i32_e32 v23, 31, v22
	v_and_b32_e32 v192, 15, v26
	v_mad_i32_i24 v25, v21, s91, v25
	v_lshl_add_u64 v[20:21], s[22:23], 0, v[22:23]
	v_mad_u64_u32 v[18:19], s[22:23], v20, s91, v[18:19]
	v_lshlrev_b32_e32 v29, 5, v191
	v_lshlrev_b32_e32 v193, 3, v192
	s_mov_b32 s25, s59
	v_lshlrev_b32_e32 v22, 4, v28
	v_mad_i32_i24 v19, v21, s91, v19
	v_xor_b32_e32 v30, v29, v193
	v_lshl_add_u64 v[20:21], v[24:25], 0, s[24:25]
	v_and_b32_e32 v22, 0x70, v22
	v_mov_b32_e32 v23, v1
	v_lshl_add_u64 v[20:21], v[20:21], 0, v[22:23]
	s_mov_b64 s[22:23], 0xa00
	v_lshl_add_u64 v[18:19], v[18:19], 0, s[24:25]
	v_lshlrev_b32_e32 v22, 1, v30
	s_lshl_b32 s17, s17, 10
	v_lshl_add_u64 v[186:187], v[20:21], 0, s[22:23]
	v_lshl_add_u64 v[18:19], v[18:19], 0, v[22:23]
	s_mov_b64 s[22:23], 0xe00
	s_add_i32 s17, s17, 0
	v_lshl_add_u64 v[188:189], v[18:19], 0, s[22:23]
	s_mov_b32 m0, s17
	s_mov_b64 s[22:23], 0xa80
	global_load_lds_dwordx4 v[186:187], off
	v_lshl_add_u64 v[22:23], v[20:21], 0, s[22:23]
	s_add_i32 m0, s17, 0x2000
	s_mov_b64 s[22:23], 0x24e00
	global_load_lds_dwordx4 v[22:23], off
	s_add_i32 m0, s17, 0x4000
	v_lshl_add_u64 v[22:23], v[18:19], 0, s[22:23]
	global_load_lds_dwordx4 v[188:189], off
	s_add_i32 m0, s17, 0x6000
	s_mov_b64 s[22:23], 0x48a00
	global_load_lds_dwordx4 v[22:23], off
	s_add_i32 m0, s17, 0x8000
	v_lshl_add_u64 v[22:23], v[20:21], 0, s[22:23]
	s_mov_b64 s[22:23], 0x48a80
	global_load_lds_dwordx4 v[22:23], off
	v_lshl_add_u64 v[22:23], v[20:21], 0, s[22:23]
	s_add_i32 m0, s17, 0xa000
	s_mov_b64 s[22:23], 0x48e00
	global_load_lds_dwordx4 v[22:23], off
	v_lshl_add_u64 v[22:23], v[18:19], 0, s[22:23]
	s_add_i32 m0, s17, 0xc000
	s_mov_b64 s[22:23], 0x6ce00
	global_load_lds_dwordx4 v[22:23], off
	v_lshl_add_u64 v[22:23], v[18:19], 0, s[22:23]
	s_add_i32 m0, s17, 0xe000
	s_mov_b64 s[22:23], 0x90a00
	global_load_lds_dwordx4 v[22:23], off
	s_add_i32 m0, s17, 0x10000
	v_lshl_add_u64 v[22:23], v[20:21], 0, s[22:23]
	s_mov_b64 s[22:23], 0x90a80
	global_load_lds_dwordx4 v[22:23], off
	v_lshl_add_u64 v[20:21], v[20:21], 0, s[22:23]
	s_add_i32 m0, s17, 0x12000
	s_mov_b64 s[22:23], 0x90e00
	global_load_lds_dwordx4 v[20:21], off
	v_lshl_add_u64 v[20:21], v[18:19], 0, s[22:23]
	s_add_i32 m0, s17, 0x14000
	s_mov_b64 s[22:23], 0xb4e00
	global_load_lds_dwordx4 v[20:21], off
	v_lshl_add_u64 v[18:19], v[18:19], 0, s[22:23]
	s_add_i32 m0, s17, 0x16000
	v_lshlrev_b32_e32 v20, 7, v195
	global_load_lds_dwordx4 v[18:19], off
	v_lshrrev_b32_e32 v18, 1, v26
	v_bfe_u32 v19, v26, 1, 3
	v_lshl_or_b32 v20, s16, 13, v20
	v_bitop3_b32 v18, v27, v18, 7 bitop3:0x78
	v_lshl_or_b32 v197, v18, 4, v20
	v_bitop3_b32 v18, v27, v19, 2 bitop3:0x36
	v_lshl_or_b32 v198, v18, 4, v20
	v_bitop3_b32 v18, v27, v19, 4 bitop3:0x36
	v_lshl_or_b32 v199, v18, 4, v20
	v_bitop3_b32 v18, v27, v19, 6 bitop3:0x36
	v_lshl_or_b32 v200, v18, 4, v20
	v_bfe_u32 v18, v26, 2, 2
	v_lshlrev_b32_e32 v19, 10, v27
	v_lshlrev_b32_e32 v20, 8, v18
	v_and_b32_e32 v21, 32, v29
	v_or3_b32 v19, v19, v20, v21
	v_lshlrev_b32_e32 v20, 3, v26
	v_and_b32_e32 v20, 24, v20
	v_lshlrev_b32_e32 v18, 6, v18
	v_or3_b32 v18, v19, v20, v18
	v_mov_b32_e32 v19, 0x4000
	s_movk_i32 s23, 0x80
	v_bitop3_b32 v207, v18, s23, v19 bitop3:0x36
	s_movk_i32 s23, 0xc0
	s_waitcnt vmcnt(8)
	s_barrier
	v_and_b32_e32 v196, 63, v26
	v_or_b32_e32 v201, 0x4000, v18
	v_bitop3_b32 v206, v18, 64, v19 bitop3:0x36
	v_bitop3_b32 v208, v18, s23, v19 bitop3:0x36
	v_add_u32_e32 v26, 0, v197
	ds_read_b128 v[18:21], v26 offset:0
	ds_read_b128 v[22:25], v26 offset:4096
	v_lshlrev_b32_e32 v194, 3, v27
	v_add_u32_e32 v34, 0, v198
	ds_read_b128 v[26:29], v34 offset:0
	ds_read_b128 v[30:33], v34 offset:4096
	v_add_u32_e32 v42, 0, v199
	ds_read_b128 v[34:37], v42 offset:0
	ds_read_b128 v[38:41], v42 offset:4096
	v_add_u32_e32 v50, 0, v200
	ds_read_b128 v[42:45], v50 offset:0
	ds_read_b128 v[46:49], v50 offset:4096
	s_waitcnt lgkmcnt(0)
	v_mov_b64_e32 v[250:251], 0x100
	v_mov_b32_e32 v215, v247
	v_mov_b32_e32 v222, 0x1200
	s_mov_b32 s22, 0x8000
	s_waitcnt vmcnt(0)
	v_mfma_f32_32x32x16_bf16 v[82:97], v[18:21], v[130:133], v[2:17]
	v_mfma_f32_32x32x16_bf16 v[98:113], v[22:25], v[130:133], v[2:17]
	v_mfma_f32_32x32x16_bf16 v[82:97], v[26:29], v[134:137], v[82:97]
	v_mfma_f32_32x32x16_bf16 v[98:113], v[30:33], v[134:137], v[98:113]
	v_mfma_f32_32x32x16_bf16 v[82:97], v[34:37], v[138:141], v[82:97]
	v_mfma_f32_32x32x16_bf16 v[98:113], v[38:41], v[138:141], v[98:113]
	v_mfma_f32_32x32x16_bf16 v[82:97], v[42:45], v[142:145], v[82:97]
	v_mfma_f32_32x32x16_bf16 v[98:113], v[46:49], v[142:145], v[98:113]
	v_mov_b32_e32 v209, 0
	s_mov_b32 s23, 0x18000
	s_mov_b32 s25, 0
	s_mov_b32 s24, 0
	v_mov_b32_e32 v66, 0
	v_mov_b32_e32 v67, v209
	v_mov_b32_e32 v68, v209
	v_mov_b32_e32 v69, v209
	v_mov_b32_e32 v70, v209
	v_mov_b32_e32 v71, v209
	v_mov_b32_e32 v72, v209
	v_mov_b32_e32 v73, v209
	v_mov_b32_e32 v74, v209
	v_mov_b32_e32 v75, v209
	v_mov_b32_e32 v76, v209
	v_mov_b32_e32 v77, v209
	v_mov_b32_e32 v78, v209
	v_mov_b32_e32 v79, v209
	v_mov_b32_e32 v80, v209
	v_mov_b32_e32 v81, v209
	v_mov_b32_e32 v50, 0
	v_mov_b32_e32 v51, v209
	v_mov_b32_e32 v52, v209
	v_mov_b32_e32 v53, v209
	v_mov_b32_e32 v54, v209
	v_mov_b32_e32 v55, v209
	v_mov_b32_e32 v56, v209
	v_mov_b32_e32 v57, v209
	v_mov_b32_e32 v58, v209
	v_mov_b32_e32 v59, v209
	v_mov_b32_e32 v60, v209
	v_mov_b32_e32 v61, v209
	v_mov_b32_e32 v62, v209
	v_mov_b32_e32 v63, v209
	v_mov_b32_e32 v64, v209
	v_mov_b32_e32 v65, v209
	v_mov_b32_e32 v34, 0
	v_mov_b32_e32 v35, v209
	v_mov_b32_e32 v36, v209
	v_mov_b32_e32 v37, v209
	v_mov_b32_e32 v38, v209
	v_mov_b32_e32 v39, v209
	v_mov_b32_e32 v40, v209
	v_mov_b32_e32 v41, v209
	v_mov_b32_e32 v42, v209
	v_mov_b32_e32 v43, v209
	v_mov_b32_e32 v44, v209
	v_mov_b32_e32 v45, v209
	v_mov_b32_e32 v46, v209
	v_mov_b32_e32 v47, v209
	v_mov_b32_e32 v48, v209
	v_mov_b32_e32 v49, v209
	v_mov_b32_e32 v18, 0
	v_mov_b32_e32 v19, v209
	v_mov_b32_e32 v20, v209
	v_mov_b32_e32 v21, v209
	v_mov_b32_e32 v22, v209
	v_mov_b32_e32 v23, v209
	v_mov_b32_e32 v24, v209
	v_mov_b32_e32 v25, v209
	v_mov_b32_e32 v26, v209
	v_mov_b32_e32 v27, v209
	v_mov_b32_e32 v28, v209
	v_mov_b32_e32 v29, v209
	v_mov_b32_e32 v30, v209
	v_mov_b32_e32 v31, v209
	v_mov_b32_e32 v32, v209
	v_mov_b32_e32 v33, v209
	v_mov_b32_e32 v223, v207
	v_mov_b32_e32 v224, v208
	ds_read_b64_tr_b16 v[162:163], v201 offset:0
	ds_read_b64_tr_b16 v[164:165], v201 offset:2048
	ds_read_b64_tr_b16 v[158:159], v206 offset:0
	ds_read_b64_tr_b16 v[160:161], v206 offset:2048
	ds_read_b64_tr_b16 v[154:155], v223 offset:0
	ds_read_b64_tr_b16 v[156:157], v223 offset:2048
	ds_read_b64_tr_b16 v[150:151], v224 offset:0
	ds_read_b64_tr_b16 v[152:153], v224 offset:2048
	v_exp_f32_e32 v226, v82
	v_exp_f32_e32 v227, v83
	v_exp_f32_e32 v228, v84
	v_exp_f32_e32 v229, v85
	v_exp_f32_e32 v230, v86
	v_exp_f32_e32 v231, v87
	v_mov_b32_e32 v170, 0
	v_mov_b32_e32 v171, 0
	v_mov_b32_e32 v172, 0
	v_mov_b32_e32 v173, 0
	v_mov_b32_e32 v246, 0
	v_mov_b32_e32 v247, 0
	v_mov_b32_e32 v248, 0
	v_mov_b32_e32 v249, 0
	v_mov_b32_e32 v202, 0
	v_mov_b32_e32 v203, 0
	v_mov_b32_e32 v204, 0
	v_mov_b32_e32 v205, 0
	v_mov_b32_e32 v210, 0
	v_mov_b32_e32 v211, 0
	v_mov_b32_e32 v212, 0
	v_mov_b32_e32 v213, 0
	v_mov_b32_e32 v216, 0
	v_mov_b32_e32 v217, 0
	v_mov_b32_e32 v218, 0
	v_mov_b32_e32 v219, 0
.LBB0_366:
	s_min_u32 s26, s24, 28
	s_mul_i32 s26, s26, 0x48000
	s_add_i32 s27, s17, s23
	s_add_i32 s58, s26, 0xd8000
	s_waitcnt vmcnt(4)
	s_barrier
	s_add_i32 s26, s22, 0
	v_add_u32_e32 v118, s26, v197
	v_add_u32_e32 v122, s26, v198
	v_add_u32_e32 v126, s26, v199
	ds_read_b128 v[114:117], v118 offset:0
	ds_read_b128 v[182:185], v118 offset:4096
	ds_read_b128 v[118:121], v122 offset:0
	ds_read_b128 v[178:181], v122 offset:4096
	ds_read_b128 v[122:125], v126 offset:0
	ds_read_b128 v[166:169], v126 offset:4096
	v_add_u32_e32 v225, s26, v200
	ds_read_b128 v[126:129], v225 offset:0
	ds_read_b128 v[146:149], v225 offset:4096
	s_add_i32 s25, s25, 0
	s_setprio 1
	v_mfma_f32_32x32x16_bf16 v[66:81], v[246:249], v[170:173], v[66:81]
	v_exp_f32_e32 v232, v88
	v_exp_f32_e32 v233, v89
	v_exp_f32_e32 v234, v90
	v_mfma_f32_32x32x16_bf16 v[50:65], v[202:205], v[170:173], v[50:65]
	v_exp_f32_e32 v235, v91
	v_exp_f32_e32 v236, v92
	v_exp_f32_e32 v237, v93
	v_mfma_f32_32x32x16_bf16 v[34:49], v[210:213], v[170:173], v[34:49]
	v_add_u32_e32 v210, s25, v201
	v_add_u32_e32 v211, s25, v206
	v_exp_f32_e32 v238, v94
	v_exp_f32_e32 v239, v95
	v_mfma_f32_32x32x16_bf16 v[18:33], v[216:219], v[170:173], v[18:33]
	v_exp_f32_e32 v240, v96
	v_exp_f32_e32 v241, v97
	v_cvt_pk_bf16_f32 v170, v226, v227
	v_cvt_pk_bf16_f32 v171, v228, v229
	v_cvt_pk_bf16_f32 v172, v230, v231
	v_cvt_pk_bf16_f32 v173, v232, v233
	v_cvt_pk_bf16_f32 v174, v234, v235
	v_cvt_pk_bf16_f32 v175, v236, v237
	v_cvt_pk_bf16_f32 v176, v238, v239
	v_cvt_pk_bf16_f32 v177, v240, v241
	s_waitcnt lgkmcnt(7)
	v_mfma_f32_32x32x16_bf16 v[82:97], v[114:117], v[130:133], v[2:17]
	v_add_f32_e32 v114, 0, v226
	v_add_f32_e32 v114, v227, v114
	v_add_f32_e32 v114, v228, v114
	v_add_f32_e32 v114, v229, v114
	v_add_f32_e32 v114, v230, v114
	v_add_f32_e32 v114, v231, v114
	v_add_f32_e32 v114, v232, v114
	s_waitcnt lgkmcnt(5)
	v_mfma_f32_32x32x16_bf16 v[82:97], v[118:121], v[134:137], v[82:97]
	v_add_f32_e32 v114, v233, v114
	v_add_f32_e32 v114, v234, v114
	v_add_f32_e32 v114, v235, v114
	v_add_f32_e32 v114, v236, v114
	v_add_f32_e32 v114, v237, v114
	v_add_f32_e32 v114, v238, v114
	v_add_f32_e32 v114, v239, v114
	v_lshl_add_u64 v[242:243], v[186:187], 0, s[58:59]
	s_mov_b32 m0, s27
	s_nop 0
	global_load_lds_dwordx4 v[242:243], off
	s_waitcnt lgkmcnt(3)
	v_mfma_f32_32x32x16_bf16 v[82:97], v[122:125], v[138:141], v[82:97]
	v_add_f32_e32 v114, v240, v114
	v_add_f32_e32 v225, v241, v114
	v_lshl_add_u64 v[242:243], v[242:243], 0, s[28:29]
	s_add_i32 m0, s27, 0x2000
	s_nop 0
	global_load_lds_dwordx4 v[242:243], off
	s_waitcnt lgkmcnt(1)
	v_mfma_f32_32x32x16_bf16 v[82:97], v[126:129], v[142:145], v[82:97]
	v_lshl_add_u64 v[242:243], v[188:189], 0, s[58:59]
	s_add_i32 m0, s27, 0x4000
	s_nop 0
	global_load_lds_dwordx4 v[242:243], off
	v_mfma_f32_32x32x16_bf16 v[114:129], v[182:185], v[130:133], v[2:17]
	v_lshl_add_u64 v[242:243], v[242:243], 0, s[34:35]
	s_add_i32 m0, s27, 0x6000
	s_nop 0
	global_load_lds_dwordx4 v[242:243], off
	v_mfma_f32_32x32x16_bf16 v[114:129], v[178:181], v[134:137], v[114:129]
	v_mfma_f32_32x32x16_bf16 v[114:129], v[166:169], v[138:141], v[114:129]
	s_setprio 0
	ds_read_b64_tr_b16 v[166:167], v210 offset:4096
	ds_read_b64_tr_b16 v[168:169], v210 offset:6144
	ds_read_b64_tr_b16 v[178:179], v211 offset:4096
	ds_read_b64_tr_b16 v[180:181], v211 offset:6144
	ds_read_b64_tr_b16 v[182:183], v223 offset:4096
	ds_read_b64_tr_b16 v[184:185], v223 offset:6144
	ds_read_b64_tr_b16 v[226:227], v224 offset:4096
	ds_read_b64_tr_b16 v[228:229], v224 offset:6144
	ds_read_b64_tr_b16 v[230:231], v210 offset:8192
	ds_read_b64_tr_b16 v[232:233], v210 offset:10240
	ds_read_b64_tr_b16 v[234:235], v211 offset:8192
	ds_read_b64_tr_b16 v[236:237], v211 offset:10240
	ds_read_b64_tr_b16 v[238:239], v223 offset:8192
	ds_read_b64_tr_b16 v[240:241], v223 offset:10240
	ds_read_b64_tr_b16 v[242:243], v224 offset:8192
	ds_read_b64_tr_b16 v[244:245], v224 offset:10240
	ds_read_b64_tr_b16 v[246:247], v210 offset:12288
	ds_read_b64_tr_b16 v[248:249], v210 offset:14336
	ds_read_b64_tr_b16 v[202:203], v211 offset:12288
	ds_read_b64_tr_b16 v[204:205], v211 offset:14336
	ds_read_b64_tr_b16 v[210:211], v223 offset:12288
	ds_read_b64_tr_b16 v[212:213], v223 offset:14336
	ds_read_b64_tr_b16 v[216:217], v224 offset:12288
	ds_read_b64_tr_b16 v[218:219], v224 offset:14336
	s_waitcnt lgkmcnt(15)
	s_setprio 1
	v_mfma_f32_32x32x16_bf16 v[66:81], v[162:165], v[170:173], v[66:81]
	v_exp_f32_e32 v162, v98
	v_exp_f32_e32 v163, v99
	s_nop 0
	v_cvt_pk_bf16_f32 v98, v162, v163
	v_mfma_f32_32x32x16_bf16 v[50:65], v[158:161], v[170:173], v[50:65]
	v_exp_f32_e32 v158, v100
	v_exp_f32_e32 v159, v101
	s_nop 0
	v_cvt_pk_bf16_f32 v99, v158, v159
	v_mfma_f32_32x32x16_bf16 v[34:49], v[154:157], v[170:173], v[34:49]
	v_exp_f32_e32 v154, v102
	v_exp_f32_e32 v155, v103
	s_nop 0
	v_cvt_pk_bf16_f32 v100, v154, v155
	v_mfma_f32_32x32x16_bf16 v[18:33], v[150:153], v[170:173], v[18:33]
	v_exp_f32_e32 v150, v104
	v_exp_f32_e32 v151, v105
	v_add_f32_e32 v152, v162, v225
	v_add_f32_e32 v152, v163, v152
	v_add_f32_e32 v152, v158, v152
	v_cvt_pk_bf16_f32 v101, v150, v151
	v_add_f32_e32 v152, v159, v152
	v_mfma_f32_32x32x16_bf16 v[66:81], v[166:169], v[174:177], v[66:81]
	v_exp_f32_e32 v106, v106
	v_exp_f32_e32 v107, v107
	v_add_f32_e32 v152, v154, v152
	v_add_f32_e32 v152, v155, v152
	v_add_f32_e32 v150, v150, v152
	v_cvt_pk_bf16_f32 v170, v106, v107
	v_add_f32_e32 v150, v151, v150
	v_mfma_f32_32x32x16_bf16 v[50:65], v[178:181], v[174:177], v[50:65]
	v_exp_f32_e32 v108, v108
	v_exp_f32_e32 v109, v109
	v_add_f32_e32 v106, v106, v150
	v_add_f32_e32 v106, v107, v106
	v_add_f32_e32 v106, v108, v106
	v_cvt_pk_bf16_f32 v171, v108, v109
	v_add_f32_e32 v106, v109, v106
	v_mfma_f32_32x32x16_bf16 v[34:49], v[182:185], v[174:177], v[34:49]
	v_exp_f32_e32 v110, v110
	v_exp_f32_e32 v111, v111
	v_add_f32_e32 v106, v110, v106
	v_cvt_pk_bf16_f32 v172, v110, v111
	v_add_f32_e32 v106, v111, v106
	v_mfma_f32_32x32x16_bf16 v[18:33], v[226:229], v[174:177], v[18:33]
	v_exp_f32_e32 v112, v112
	v_exp_f32_e32 v113, v113
	v_add_f32_e32 v106, v112, v106
	v_cvt_pk_bf16_f32 v173, v112, v113
	v_add_f32_e32 v106, v113, v106
	v_mfma_f32_32x32x16_bf16 v[114:129], v[146:149], v[142:145], v[114:129]
	s_waitcnt lgkmcnt(0)
	v_mfma_f32_32x32x16_bf16 v[66:81], v[230:233], v[98:101], v[66:81]
	v_add_f32_e32 v209, v209, v106
	v_add_u32_e32 v106, s22, v201
	v_add_u32_e32 v107, s22, v206
	ds_read_b64_tr_b16 v[162:163], v106 offset:0
	ds_read_b64_tr_b16 v[164:165], v106 offset:2048
	ds_read_b64_tr_b16 v[158:159], v107 offset:0
	ds_read_b64_tr_b16 v[160:161], v107 offset:2048
	v_mfma_f32_32x32x16_bf16 v[50:65], v[234:237], v[98:101], v[50:65]
	v_exp_f32_e32 v226, v82
	v_exp_f32_e32 v227, v83
	v_exp_f32_e32 v228, v84
	v_mfma_f32_32x32x16_bf16 v[34:49], v[238:241], v[98:101], v[34:49]
	v_add_u32_e32 v223, s22, v207
	v_add_u32_e32 v224, s22, v208
	ds_read_b64_tr_b16 v[154:155], v223 offset:0
	ds_read_b64_tr_b16 v[156:157], v223 offset:2048
	ds_read_b64_tr_b16 v[150:151], v224 offset:0
	ds_read_b64_tr_b16 v[152:153], v224 offset:2048
	v_mfma_f32_32x32x16_bf16 v[18:33], v[242:245], v[98:101], v[18:33]
	v_exp_f32_e32 v229, v85
	v_exp_f32_e32 v230, v86
	v_exp_f32_e32 v231, v87
	s_setprio 0
	s_add_i32 s26, s22, 0x8000
	s_cmp_lg_u32 s22, 0x18000
	s_mov_b32 s25, s22
	s_cselect_b32 s22, s26, 0
	s_add_i32 s26, s23, 0x8000
	s_cmp_lg_u32 s23, 0x18000
	s_cselect_b32 s23, s26, 0
	s_add_i32 s24, s24, 1
	s_min_u32 s26, s24, 28
	s_mul_i32 s26, s26, 0x48000
	s_add_i32 s27, s17, s23
	s_add_i32 s58, s26, 0xd8000
	s_waitcnt vmcnt(4)
	s_barrier
	s_add_i32 s26, s22, 0
	v_add_u32_e32 v102, s26, v197
	v_add_u32_e32 v106, s26, v198
	v_add_u32_e32 v110, s26, v199
	ds_read_b128 v[98:101], v102 offset:0
	ds_read_b128 v[182:185], v102 offset:4096
	ds_read_b128 v[102:105], v106 offset:0
	ds_read_b128 v[178:181], v106 offset:4096
	ds_read_b128 v[106:109], v110 offset:0
	ds_read_b128 v[166:169], v110 offset:4096
	v_add_u32_e32 v225, s26, v200
	ds_read_b128 v[110:113], v225 offset:0
	ds_read_b128 v[146:149], v225 offset:4096
	s_add_i32 s25, s25, 0
	s_setprio 1
	v_mfma_f32_32x32x16_bf16 v[66:81], v[246:249], v[170:173], v[66:81]
	v_exp_f32_e32 v232, v88
	v_exp_f32_e32 v233, v89
	v_exp_f32_e32 v234, v90
	v_mfma_f32_32x32x16_bf16 v[50:65], v[202:205], v[170:173], v[50:65]
	v_exp_f32_e32 v235, v91
	v_exp_f32_e32 v236, v92
	v_exp_f32_e32 v237, v93
	v_mfma_f32_32x32x16_bf16 v[34:49], v[210:213], v[170:173], v[34:49]
	v_add_u32_e32 v210, s25, v201
	v_add_u32_e32 v211, s25, v206
	v_exp_f32_e32 v238, v94
	v_exp_f32_e32 v239, v95
	v_mfma_f32_32x32x16_bf16 v[18:33], v[216:219], v[170:173], v[18:33]
	v_exp_f32_e32 v240, v96
	v_exp_f32_e32 v241, v97
	v_cvt_pk_bf16_f32 v170, v226, v227
	v_cvt_pk_bf16_f32 v171, v228, v229
	v_cvt_pk_bf16_f32 v172, v230, v231
	v_cvt_pk_bf16_f32 v173, v232, v233
	v_cvt_pk_bf16_f32 v174, v234, v235
	v_cvt_pk_bf16_f32 v175, v236, v237
	v_cvt_pk_bf16_f32 v176, v238, v239
	v_cvt_pk_bf16_f32 v177, v240, v241
	s_waitcnt lgkmcnt(7)
	v_mfma_f32_32x32x16_bf16 v[82:97], v[98:101], v[130:133], v[2:17]
	v_add_f32_e32 v98, 0, v226
	v_add_f32_e32 v98, v227, v98
	v_add_f32_e32 v98, v228, v98
	v_add_f32_e32 v98, v229, v98
	v_add_f32_e32 v98, v230, v98
	v_add_f32_e32 v98, v231, v98
	v_add_f32_e32 v98, v232, v98
	s_waitcnt lgkmcnt(5)
	v_mfma_f32_32x32x16_bf16 v[82:97], v[102:105], v[134:137], v[82:97]
	v_add_f32_e32 v98, v233, v98
	v_add_f32_e32 v98, v234, v98
	v_add_f32_e32 v98, v235, v98
	v_add_f32_e32 v98, v236, v98
	v_add_f32_e32 v98, v237, v98
	v_add_f32_e32 v98, v238, v98
	v_add_f32_e32 v98, v239, v98
	v_lshl_add_u64 v[242:243], v[186:187], 0, s[58:59]
	s_mov_b32 m0, s27
	s_nop 0
	global_load_lds_dwordx4 v[242:243], off
	s_waitcnt lgkmcnt(3)
	v_mfma_f32_32x32x16_bf16 v[82:97], v[106:109], v[138:141], v[82:97]
	v_add_f32_e32 v98, v240, v98
	v_add_f32_e32 v225, v241, v98
	v_lshl_add_u64 v[242:243], v[242:243], 0, s[28:29]
	s_add_i32 m0, s27, 0x2000
	s_nop 0
	global_load_lds_dwordx4 v[242:243], off
	s_waitcnt lgkmcnt(1)
	v_mfma_f32_32x32x16_bf16 v[82:97], v[110:113], v[142:145], v[82:97]
	v_lshl_add_u64 v[242:243], v[188:189], 0, s[58:59]
	s_add_i32 m0, s27, 0x4000
	s_nop 0
	global_load_lds_dwordx4 v[242:243], off
	v_mfma_f32_32x32x16_bf16 v[98:113], v[182:185], v[130:133], v[2:17]
	v_lshl_add_u64 v[242:243], v[242:243], 0, s[34:35]
	s_add_i32 m0, s27, 0x6000
	s_nop 0
	global_load_lds_dwordx4 v[242:243], off
	v_mfma_f32_32x32x16_bf16 v[98:113], v[178:181], v[134:137], v[98:113]
	v_mfma_f32_32x32x16_bf16 v[98:113], v[166:169], v[138:141], v[98:113]
	s_setprio 0
	ds_read_b64_tr_b16 v[166:167], v210 offset:4096
	ds_read_b64_tr_b16 v[168:169], v210 offset:6144
	ds_read_b64_tr_b16 v[178:179], v211 offset:4096
	ds_read_b64_tr_b16 v[180:181], v211 offset:6144
	ds_read_b64_tr_b16 v[182:183], v223 offset:4096
	ds_read_b64_tr_b16 v[184:185], v223 offset:6144
	ds_read_b64_tr_b16 v[226:227], v224 offset:4096
	ds_read_b64_tr_b16 v[228:229], v224 offset:6144
	ds_read_b64_tr_b16 v[230:231], v210 offset:8192
	ds_read_b64_tr_b16 v[232:233], v210 offset:10240
	ds_read_b64_tr_b16 v[234:235], v211 offset:8192
	ds_read_b64_tr_b16 v[236:237], v211 offset:10240
	ds_read_b64_tr_b16 v[238:239], v223 offset:8192
	ds_read_b64_tr_b16 v[240:241], v223 offset:10240
	ds_read_b64_tr_b16 v[242:243], v224 offset:8192
	ds_read_b64_tr_b16 v[244:245], v224 offset:10240
	ds_read_b64_tr_b16 v[246:247], v210 offset:12288
	ds_read_b64_tr_b16 v[248:249], v210 offset:14336
	ds_read_b64_tr_b16 v[202:203], v211 offset:12288
	ds_read_b64_tr_b16 v[204:205], v211 offset:14336
	ds_read_b64_tr_b16 v[210:211], v223 offset:12288
	ds_read_b64_tr_b16 v[212:213], v223 offset:14336
	ds_read_b64_tr_b16 v[216:217], v224 offset:12288
	ds_read_b64_tr_b16 v[218:219], v224 offset:14336
	s_waitcnt lgkmcnt(15)
	s_setprio 1
	v_mfma_f32_32x32x16_bf16 v[66:81], v[162:165], v[170:173], v[66:81]
	v_exp_f32_e32 v162, v114
	v_exp_f32_e32 v163, v115
	s_nop 0
	v_cvt_pk_bf16_f32 v114, v162, v163
	v_mfma_f32_32x32x16_bf16 v[50:65], v[158:161], v[170:173], v[50:65]
	v_exp_f32_e32 v158, v116
	v_exp_f32_e32 v159, v117
	s_nop 0
	v_cvt_pk_bf16_f32 v115, v158, v159
	v_mfma_f32_32x32x16_bf16 v[34:49], v[154:157], v[170:173], v[34:49]
	v_exp_f32_e32 v154, v118
	v_exp_f32_e32 v155, v119
	s_nop 0
	v_cvt_pk_bf16_f32 v116, v154, v155
	v_mfma_f32_32x32x16_bf16 v[18:33], v[150:153], v[170:173], v[18:33]
	v_exp_f32_e32 v150, v120
	v_exp_f32_e32 v151, v121
	v_add_f32_e32 v152, v162, v225
	v_add_f32_e32 v152, v163, v152
	v_add_f32_e32 v152, v158, v152
	v_cvt_pk_bf16_f32 v117, v150, v151
	v_add_f32_e32 v152, v159, v152
	v_mfma_f32_32x32x16_bf16 v[66:81], v[166:169], v[174:177], v[66:81]
	v_exp_f32_e32 v122, v122
	v_exp_f32_e32 v123, v123
	v_add_f32_e32 v152, v154, v152
	v_add_f32_e32 v152, v155, v152
	v_add_f32_e32 v150, v150, v152
	v_cvt_pk_bf16_f32 v170, v122, v123
	v_add_f32_e32 v150, v151, v150
	v_mfma_f32_32x32x16_bf16 v[50:65], v[178:181], v[174:177], v[50:65]
	v_exp_f32_e32 v124, v124
	v_exp_f32_e32 v125, v125
	v_add_f32_e32 v122, v122, v150
	v_add_f32_e32 v122, v123, v122
	v_add_f32_e32 v122, v124, v122
	v_cvt_pk_bf16_f32 v171, v124, v125
	v_add_f32_e32 v122, v125, v122
	v_mfma_f32_32x32x16_bf16 v[34:49], v[182:185], v[174:177], v[34:49]
	v_exp_f32_e32 v126, v126
	v_exp_f32_e32 v127, v127
	v_add_f32_e32 v122, v126, v122
	v_cvt_pk_bf16_f32 v172, v126, v127
	v_add_f32_e32 v122, v127, v122
	v_mfma_f32_32x32x16_bf16 v[18:33], v[226:229], v[174:177], v[18:33]
	v_exp_f32_e32 v128, v128
	v_exp_f32_e32 v129, v129
	v_add_f32_e32 v122, v128, v122
	v_cvt_pk_bf16_f32 v173, v128, v129
	v_add_f32_e32 v122, v129, v122
	v_mfma_f32_32x32x16_bf16 v[98:113], v[146:149], v[142:145], v[98:113]
	s_waitcnt lgkmcnt(0)
	v_mfma_f32_32x32x16_bf16 v[66:81], v[230:233], v[114:117], v[66:81]
	v_add_f32_e32 v209, v209, v122
	v_add_u32_e32 v122, s22, v201
	v_add_u32_e32 v123, s22, v206
	ds_read_b64_tr_b16 v[162:163], v122 offset:0
	ds_read_b64_tr_b16 v[164:165], v122 offset:2048
	ds_read_b64_tr_b16 v[158:159], v123 offset:0
	ds_read_b64_tr_b16 v[160:161], v123 offset:2048
	v_mfma_f32_32x32x16_bf16 v[50:65], v[234:237], v[114:117], v[50:65]
	v_exp_f32_e32 v226, v82
	v_exp_f32_e32 v227, v83
	v_exp_f32_e32 v228, v84
	v_mfma_f32_32x32x16_bf16 v[34:49], v[238:241], v[114:117], v[34:49]
	v_add_u32_e32 v223, s22, v207
	v_add_u32_e32 v224, s22, v208
	ds_read_b64_tr_b16 v[154:155], v223 offset:0
	ds_read_b64_tr_b16 v[156:157], v223 offset:2048
	ds_read_b64_tr_b16 v[150:151], v224 offset:0
	ds_read_b64_tr_b16 v[152:153], v224 offset:2048
	v_mfma_f32_32x32x16_bf16 v[18:33], v[242:245], v[114:117], v[18:33]
	v_exp_f32_e32 v229, v85
	v_exp_f32_e32 v230, v86
	v_exp_f32_e32 v231, v87
	s_setprio 0
	s_add_i32 s26, s22, 0x8000
	s_cmp_lg_u32 s22, 0x18000
	s_mov_b32 s25, s22
	s_cselect_b32 s22, s26, 0
	s_add_i32 s26, s23, 0x8000
	s_cmp_lg_u32 s23, 0x18000
	s_cselect_b32 s23, s26, 0
	s_add_i32 s24, s24, 1
	s_cmp_eq_u32 s24, 32
	s_cbranch_scc0 .LBB0_366
	s_waitcnt lgkmcnt(0)
	v_mfma_f32_32x32x16_bf16 v[66:81], v[246:249], v[170:173], v[66:81]
	v_mfma_f32_32x32x16_bf16 v[50:65], v[202:205], v[170:173], v[50:65]
	v_mfma_f32_32x32x16_bf16 v[34:49], v[210:213], v[170:173], v[34:49]
	v_mfma_f32_32x32x16_bf16 v[18:33], v[216:219], v[170:173], v[18:33]
	s_nop 15
	global_load_dwordx4 v[98:101], v0, s[10:11]
	global_load_dwordx4 v[102:105], v0, s[10:11] offset:32
	global_load_dwordx4 v[106:109], v0, s[10:11] offset:64
	global_load_dwordx4 v[110:113], v0, s[10:11] offset:96
	global_load_dwordx4 v[114:117], v0, s[10:11] offset:128
	global_load_dwordx4 v[118:121], v0, s[10:11] offset:160
	global_load_dwordx4 v[122:125], v0, s[10:11] offset:192
	global_load_dwordx4 v[126:129], v0, s[10:11] offset:224
	global_load_dwordx4 v[130:133], v0, s[10:11] offset:256
	global_load_dwordx4 v[134:137], v0, s[10:11] offset:288
	global_load_dwordx4 v[138:141], v0, s[10:11] offset:320
	global_load_dwordx4 v[142:145], v0, s[10:11] offset:352
	global_load_dwordx4 v[146:149], v0, s[10:11] offset:384
	global_load_dwordx4 v[150:153], v0, s[10:11] offset:416
	global_load_dwordx4 v[154:157], v0, s[10:11] offset:448
	global_load_dwordx4 v[158:161], v0, s[10:11] offset:480
	ds_bpermute_b32 v82, v221, v209
	s_lshl_b32 s17, s21, 14
	s_add_i32 s17, s17, 0
	s_waitcnt vmcnt(0)
	s_cmp_eq_u32 s16, 0
	s_waitcnt lgkmcnt(0)
	v_add_f32_e32 v82, v209, v82
	v_div_scale_f32 v83, s[22:23], v82, v82, 1.0
	v_rcp_f32_e32 v84, v83
	v_div_scale_f32 v85, vcc, 1.0, v82, 1.0
	v_lshl_add_u32 v92, v196, 4, s17
	v_fma_f32 v86, -v83, v84, 1.0
	v_fmac_f32_e32 v84, v86, v84
	v_mul_f32_e32 v86, v85, v84
	v_fma_f32 v87, -v83, v86, v85
	v_fmac_f32_e32 v86, v87, v84
	v_fma_f32 v83, -v83, v86, v85
	v_div_fmas_f32 v83, v83, v84, v86
	s_cselect_b64 s[16:17], -1, 0
	v_div_fixup_f32 v82, v83, v82, 1.0
	s_and_b64 vcc, exec, s[16:17]
	s_waitcnt vmcnt(0)
	s_barrier
	s_cbranch_vccnz .LBB0_369
	v_pk_mul_f32 v[86:87], v[68:69], v[82:83] op_sel_hi:[1,0]
	v_pk_mul_f32 v[84:85], v[66:67], v[82:83] op_sel_hi:[1,0]
	ds_write_b128 v92, v[84:87]
	v_pk_mul_f32 v[86:87], v[72:73], v[82:83] op_sel_hi:[1,0]
	v_pk_mul_f32 v[84:85], v[70:71], v[82:83] op_sel_hi:[1,0]
	ds_write_b128 v92, v[84:87] offset:1024
	v_pk_mul_f32 v[86:87], v[76:77], v[82:83] op_sel_hi:[1,0]
	v_pk_mul_f32 v[84:85], v[74:75], v[82:83] op_sel_hi:[1,0]
	ds_write_b128 v92, v[84:87] offset:2048
	v_pk_mul_f32 v[86:87], v[80:81], v[82:83] op_sel_hi:[1,0]
	v_pk_mul_f32 v[84:85], v[78:79], v[82:83] op_sel_hi:[1,0]
	ds_write_b128 v92, v[84:87] offset:3072
	v_pk_mul_f32 v[86:87], v[52:53], v[82:83] op_sel_hi:[1,0]
	v_pk_mul_f32 v[84:85], v[50:51], v[82:83] op_sel_hi:[1,0]
	ds_write_b128 v92, v[84:87] offset:4096
	v_pk_mul_f32 v[86:87], v[56:57], v[82:83] op_sel_hi:[1,0]
	v_pk_mul_f32 v[84:85], v[54:55], v[82:83] op_sel_hi:[1,0]
	ds_write_b128 v92, v[84:87] offset:5120
	v_pk_mul_f32 v[86:87], v[60:61], v[82:83] op_sel_hi:[1,0]
	v_pk_mul_f32 v[84:85], v[58:59], v[82:83] op_sel_hi:[1,0]
	ds_write_b128 v92, v[84:87] offset:6144
	v_pk_mul_f32 v[86:87], v[64:65], v[82:83] op_sel_hi:[1,0]
	v_pk_mul_f32 v[84:85], v[62:63], v[82:83] op_sel_hi:[1,0]
	ds_write_b128 v92, v[84:87] offset:7168
	v_pk_mul_f32 v[86:87], v[36:37], v[82:83] op_sel_hi:[1,0]
	v_pk_mul_f32 v[84:85], v[34:35], v[82:83] op_sel_hi:[1,0]
	ds_write_b128 v92, v[84:87] offset:8192
	v_pk_mul_f32 v[86:87], v[40:41], v[82:83] op_sel_hi:[1,0]
	v_pk_mul_f32 v[84:85], v[38:39], v[82:83] op_sel_hi:[1,0]
	ds_write_b128 v92, v[84:87] offset:9216
	v_pk_mul_f32 v[86:87], v[44:45], v[82:83] op_sel_hi:[1,0]
	v_pk_mul_f32 v[84:85], v[42:43], v[82:83] op_sel_hi:[1,0]
	ds_write_b128 v92, v[84:87] offset:10240
	v_pk_mul_f32 v[86:87], v[48:49], v[82:83] op_sel_hi:[1,0]
	v_pk_mul_f32 v[84:85], v[46:47], v[82:83] op_sel_hi:[1,0]
	ds_write_b128 v92, v[84:87] offset:11264
	v_pk_mul_f32 v[86:87], v[20:21], v[82:83] op_sel_hi:[1,0]
	v_pk_mul_f32 v[84:85], v[18:19], v[82:83] op_sel_hi:[1,0]
	ds_write_b128 v92, v[84:87] offset:12288
	v_pk_mul_f32 v[86:87], v[24:25], v[82:83] op_sel_hi:[1,0]
	v_pk_mul_f32 v[84:85], v[22:23], v[82:83] op_sel_hi:[1,0]
	ds_write_b128 v92, v[84:87] offset:13312
	v_pk_mul_f32 v[86:87], v[28:29], v[82:83] op_sel_hi:[1,0]
	v_pk_mul_f32 v[84:85], v[26:27], v[82:83] op_sel_hi:[1,0]
	ds_write_b128 v92, v[84:87] offset:14336
	v_pk_mul_f32 v[86:87], v[32:33], v[82:83] op_sel_hi:[1,0]
	v_pk_mul_f32 v[84:85], v[30:31], v[82:83] op_sel_hi:[1,0]
	ds_write_b128 v92, v[84:87] offset:15360
